# unit-index division by shift/mask; row rstd in P4/P8 epilogues computed cooperatively across column groups with ds_bpermute exchange
# speedup vs baseline: 1.0145x; 1.0145x over previous
;     __host__ __device__ bool next(int i, Unit& u) const { if (!b.next(i >> 1, u)) return false; u.sel = i & 1; return true; }
;     __host__ __device__ bool next(int i, Unit& u) const {
;         const long L = (long)i * G + c; if (L >= nwg) return false;
;         int wgid = (int)L; { const int q = nwg / NXCD, r = nwg % NXCD, xcd = wgid % NXCD, off = wgid / NXCD; wgid = (xcd < r ? xcd * (q + 1) : r * (q + 1) + (xcd - r) * q) + off; }
;         const int nig = WGM * nN, gid = wgid / nig, fm = gid * WGM, gsz = (nM - fm) < WGM ? (nM - fm) : WGM;
;         u.pm = fm + ((wgid % nig) % gsz); u.pn = (wgid % nig) / gsz; u.sel = 0; return true;
.LBB0_205:
	s_add_i32 s44, s44, 1
	s_mul_i32 s0, s44, s46
	s_mul_hi_u32 s1, s44, s33
	s_add_i32 s1, s1, s0
	s_mul_i32 s0, s44, s33
	s_add_u32 s16, s0, s87
	s_addc_u32 s17, s1, s35
	v_cmp_gt_i64_e32 vcc, s[16:17], v[146:147]
	v_cmp_lt_i64_e64 s[0:1], s[16:17], v[144:145]
	s_cbranch_vccnz .LBB0_207
	s_ashr_i32 s12, s16, 31
	s_lshr_b32 s12, s12, 29
	s_add_i32 s12, s16, s12
	s_ashr_i32 s13, s12, 3
	s_and_b32 s12, s12, -8
	s_sub_i32 s12, s16, s12
	s_cmp_lt_i32 s12, 0
	s_cselect_b32 s14, s36, 0x160
	s_mul_i32 s12, s12, s14
	s_add_i32 s12, s12, s13
	s_mul_hi_i32 s13, s12, 0x2e8ba2e9
	s_lshr_b32 s14, s13, 31
	s_ashr_i32 s13, s13, 3
	s_add_i32 s13, s13, s14
	s_lshl_b32 s14, s13, 1
	s_mul_i32 s13, s13, 44
	s_sub_i32 s13, s12, s13
	s_lshr_b32 s12, s13, 1
	s_and_b32 s13, s13, 1
	s_add_i32 s14, s14, s13

;     __host__ __device__ bool next(int i, Unit& u) const { if (!b.next(i >> 1, u)) return false; u.sel = i & 1; return true; }
;     __host__ __device__ bool next(int i, Unit& u) const {
;         const long L = (long)i * G + c; if (L >= nwg) return false;
;         int wgid = (int)L; { const int q = nwg / NXCD, r = nwg % NXCD, xcd = wgid % NXCD, off = wgid / NXCD; wgid = (xcd < r ? xcd * (q + 1) : r * (q + 1) + (xcd - r) * q) + off; }
;         const int nig = WGM * nN, gid = wgid / nig, fm = gid * WGM, gsz = (nM - fm) < WGM ? (nM - fm) : WGM;
;         u.pm = fm + ((wgid % nig) % gsz); u.pn = (wgid % nig) / gsz; u.sel = 0; return true;
.LBB0_283:
	s_ashr_i32 s2, s30, 3
	s_add_i32 s2, s34, s2
	s_ashr_i32 s3, s2, 31
	s_lshr_b32 s3, s3, 29
	s_add_i32 s3, s2, s3
	s_ashr_i32 s30, s3, 3
	s_lshl_b32 s30, s30, 1
	s_and_b32 s3, s3, -8
	s_sub_i32 s2, s2, s3
	s_lshr_b32 s71, s2, 1
	s_and_b32 s2, s2, 1
	s_add_i32 s72, s30, s2

;     __host__ __device__ bool next(int i, Unit& u) const { if (!b.next(i >> 1, u)) return false; u.sel = i & 1; return true; }
;     __host__ __device__ bool next(int i, Unit& u) const {
;         const long L = (long)i * G + c; if (L >= nwg) return false;
;         int wgid = (int)L; { const int q = nwg / NXCD, r = nwg % NXCD, xcd = wgid % NXCD, off = wgid / NXCD; wgid = (xcd < r ? xcd * (q + 1) : r * (q + 1) + (xcd - r) * q) + off; }
;         const int nig = WGM * nN, gid = wgid / nig, fm = gid * WGM, gsz = (nM - fm) < WGM ? (nM - fm) : WGM;
;         u.pm = fm + ((wgid % nig) % gsz); u.pn = (wgid % nig) / gsz; u.sel = 0; return true;
.LBB0_435:
	s_add_i32 s15, s15, 1
	s_mul_i32 s2, s15, s86
	s_mul_hi_u32 s3, s15, s33
	s_add_i32 s3, s3, s2
	s_mul_i32 s2, s15, s33
	v_readlane_b32 s5, v254, 12
	s_add_u32 s8, s2, s5
	s_addc_u32 s9, s3, s87
	v_cmp_gt_i64_e32 vcc, s[8:9], v[194:195]
	v_cmp_lt_i64_e64 s[2:3], s[8:9], v[192:193]
	s_cbranch_vccnz .LBB0_437
	s_ashr_i32 s5, s8, 31
	s_lshr_b32 s5, s5, 29
	s_add_i32 s5, s8, s5
	s_ashr_i32 s7, s5, 3
	s_and_b32 s5, s5, -8
	s_sub_i32 s5, s8, s5
	s_cmp_lt_i32 s5, 0
	s_movk_i32 s8, 0x1a1
	s_cselect_b32 s8, s8, 0x1a0
	s_mul_i32 s5, s5, s8
	s_add_i32 s5, s5, s7
	s_mul_hi_i32 s7, s5, 0x4ec4ec4f
	s_lshr_b32 s8, s7, 31
	s_ashr_i32 s7, s7, 4
	s_add_i32 s7, s7, s8
	s_lshl_b32 s8, s7, 1
	s_mul_i32 s7, s7, 52
	s_sub_i32 s5, s5, s7
	s_lshr_b32 s44, s5, 1
	s_and_b32 s5, s5, 1
	s_add_i32 s46, s8, s5

; #define PG8_LAS __attribute__((address_space(3)))
; #define EPI_ROWS _Pragma("unroll") for (int ai = 0; ai < 2; ++ai) _Pragma("unroll") for (int m = 0; m < 4; ++m)
; __device__ __forceinline__ float rstd_lds(const PG8_LAS unsigned char* scr, int lrow) {
;     const PG8_LAS f32x4* p = (const PG8_LAS f32x4*)(scr + lrow * 64);
;     const f32x4 s = (p[0] + p[1]) + (p[2] + p[3]);
;     return __builtin_amdgcn_rsqf(((s[0] + s[1]) + (s[2] + s[3])) * (1.0f / DM) + RMS_EPS);
; }
;     __device__ __forceinline__ void operator()(const f32x4 (&acc)[2][2][4][2], const Unit& u, int wr, int wc, int fr, int fq) const {
;     ...
;         float rsv[2][4];
;         EPI_ROWS { rsv[ai][m] = rstd_lds(scr, EPI_LROW); asm volatile("" : "+v"(rsv[ai][m]) :: "memory"); }
;     ...
; #pragma unroll
;         for (int r = 0; r < 8; ++r) { const int ai = r >> 2, m = r & 3; const int row = EPI_ROW; const float rs = rsv[ai][m];
;             f32x4 a0 = acc[ai][0][m][0] * rs + ba0, a1 = acc[ai][0][m][1] * rs + ba1, b0 = acc[ai][1][m][0] * rs + bb0, b1 = acc[ai][1][m][1] * rs + bb1;
.LBB0_462:
	v_lshlrev_b32_e32 v165, 6, v175
	v_lshl_add_u32 v146, v147, 10, v165
	v_add_u32_e32 v146, s89, v146
	ds_read_b128 v[148:151], v146
	ds_read_b128 v[152:155], v146 offset:16
	ds_read_b128 v[156:159], v146 offset:32
	ds_read_b128 v[160:163], v146 offset:48
	ds_read_b128 v[230:233], v146 offset:8192
	ds_read_b128 v[234:237], v146 offset:8208
	ds_read_b128 v[238:241], v146 offset:8224
	ds_read_b128 v[242:245], v146 offset:8240
	v_lshlrev_b32_e32 v197, 4, v147
	v_add_u32_e32 v147, v197, v175
	v_lshlrev_b32_e32 v177, 4, v147
	v_ashrrev_i32_e32 v147, 3, v147
	s_lshl_b32 s31, s4, 8
	v_mad_u64_u32 v[172:173], s[4:5], s52, v147, 0
	s_add_i32 s8, s84, s8
	s_ashr_i32 s9, s8, 31
	s_xor_b64 s[56:57], s[56:57], -1
	s_add_i32 s31, s31, s79
	s_mov_b64 s[60:61], -1
	s_xor_b64 s[58:59], s[58:59], -1
	v_cmp_gt_u32_e64 s[6:7], 8, v175
	v_add_u32_e32 v212, s31, v175
	v_ashrrev_i32_e32 v165, 31, v164
	s_and_b64 vcc, exec, s[56:57]
	s_waitcnt lgkmcnt(4)
	v_pk_add_f32 v[150:151], v[150:151], v[154:155]
	v_pk_add_f32 v[148:149], v[148:149], v[152:153]
	v_pk_add_f32 v[152:153], v[158:159], v[162:163]
	v_pk_add_f32 v[154:155], v[156:157], v[160:161]
	v_pk_add_f32 v[150:151], v[150:151], v[152:153]
	v_pk_add_f32 v[148:149], v[148:149], v[154:155]
	v_add_f32_e32 v148, v148, v149
	v_add_f32_e32 v150, v150, v151
	v_add_f32_e32 v148, v148, v150
	v_fmamk_f32 v148, v148, 0x3a800000, v211
	v_rsq_f32_e32 v148, v148
	s_waitcnt lgkmcnt(0)
	v_pk_add_f32 v[232:233], v[232:233], v[236:237]
	v_pk_add_f32 v[230:231], v[230:231], v[234:235]
	v_pk_add_f32 v[234:235], v[240:241], v[244:245]
	v_pk_add_f32 v[236:237], v[238:239], v[242:243]
	v_pk_add_f32 v[232:233], v[232:233], v[234:235]
	v_pk_add_f32 v[230:231], v[230:231], v[236:237]
	v_add_f32_e32 v230, v230, v231
	v_add_f32_e32 v232, v232, v233
	v_add_f32_e32 v230, v230, v232
	v_fmamk_f32 v230, v230, 0x3a800000, v211
	v_rsq_f32_e32 v230, v230
	v_lshlrev_b32_e32 v149, 2, v175
	v_add_u32_e32 v150, 0x40, v149
	v_add_u32_e32 v151, 0x80, v149
	v_add_u32_e32 v153, 0xc0, v149
	ds_bpermute_b32 v146, v149, v148
	ds_bpermute_b32 v206, v150, v148
	ds_bpermute_b32 v202, v151, v148
	ds_bpermute_b32 v200, v153, v148
	ds_bpermute_b32 v198, v149, v230
	ds_bpermute_b32 v196, v150, v230
	ds_bpermute_b32 v176, v151, v230
	ds_bpermute_b32 v174, v153, v230
	s_waitcnt lgkmcnt(0)
	v_sub_u32_e32 v148, v204, v164
	v_lshlrev_b32_e32 v150, 7, v175
	v_ashrrev_i32_e32 v149, 31, v148
	v_and_b32_e32 v199, 0x380, v150
	v_lshlrev_b32_e32 v150, 4, v175
	v_lshl_add_u64 v[148:149], v[148:149], 1, s[10:11]
	v_and_b32_e32 v186, 0x70, v150
	v_lshl_add_u64 v[170:171], v[148:149], 0, v[186:187]
	v_ashrrev_i32_e32 v148, 31, v147
	v_mul_lo_u32 v148, s52, v148
	v_mul_lo_u32 v149, s53, v147
	v_add3_u32 v173, v173, v148, v149
	v_and_b32_e32 v148, -8, v175
	v_add_u32_e32 v147, 8, v147
	v_cmp_eq_u32_e64 s[4:5], 8, v148
	v_ashrrev_i32_e32 v148, 31, v147
	v_mul_lo_u32 v148, s52, v148
	v_mul_lo_u32 v149, s53, v147
	v_mad_u64_u32 v[168:169], s[28:29], s52, v147, 0
	v_lshlrev_b32_e32 v147, 5, v175
	v_add3_u32 v169, v169, v148, v149
	v_and_b32_e32 v186, 32, v147
	v_lshl_add_u64 v[148:149], v[164:165], 0, s[8:9]
	v_lshl_add_u64 v[166:167], v[148:149], 0, v[186:187]
	v_pk_fma_f32 v[144:145], v[144:145], v[146:147], v[56:57] op_sel_hi:[1,0,1]
	v_pk_fma_f32 v[142:143], v[142:143], v[146:147], v[54:55] op_sel_hi:[1,0,1]
	v_pk_fma_f32 v[140:141], v[140:141], v[146:147], v[52:53] op_sel_hi:[1,0,1]
	v_pk_fma_f32 v[138:139], v[138:139], v[146:147], v[50:51] op_sel_hi:[1,0,1]
	v_pk_fma_f32 v[136:137], v[136:137], v[146:147], v[48:49] op_sel_hi:[1,0,1]
	v_pk_fma_f32 v[134:135], v[134:135], v[146:147], v[46:47] op_sel_hi:[1,0,1]
	v_pk_fma_f32 v[132:133], v[132:133], v[146:147], v[44:45] op_sel_hi:[1,0,1]
	v_pk_fma_f32 v[130:131], v[130:131], v[146:147], v[42:43] op_sel_hi:[1,0,1]
	s_cbranch_vccz .LBB0_474
	s_mov_b64 s[8:9], -1
	s_and_b64 vcc, exec, s[58:59]
	s_cbranch_vccz .LBB0_471
	v_mov_b64_e32 v[154:155], v[132:133]
	v_mov_b64_e32 v[158:159], v[136:137]
	v_mov_b64_e32 v[150:151], v[140:141]
	v_mov_b64_e32 v[162:163], v[144:145]
	s_andn2_b64 vcc, exec, s[54:55]
	v_mov_b64_e32 v[152:153], v[130:131]
	v_mov_b64_e32 v[156:157], v[134:135]
	v_mov_b64_e32 v[148:149], v[138:139]
	v_mov_b64_e32 v[160:161], v[142:143]
	s_cbranch_vccnz .LBB0_466
	s_mov_b64 s[98:99], 0x800
	s_mov_b64 s[100:101], 0x2800
	v_lshlrev_b32_e32 v146, 7, v212
	v_and_b32_e32 v186, 0xfff80, v146
	v_lshlrev_b64 v[154:155], 2, v[164:165]
	v_lshl_add_u64 v[146:147], s[20:21], 0, v[186:187]
	v_lshl_add_u64 v[150:151], v[146:147], 0, v[154:155]
	v_mov_b64_e32 v[246:247], v[150:151]
	v_lshl_add_u64 v[156:157], s[18:19], 0, v[186:187]
	global_load_dwordx4 v[146:149], v[150:151], off
	s_nop 0
	global_load_dwordx4 v[150:153], v[150:151], off offset:16
	v_lshl_add_u64 v[158:159], v[156:157], 0, v[154:155]
	v_mov_b64_e32 v[248:249], v[158:159]
	global_load_dwordx4 v[154:157], v[158:159], off
	global_load_dwordx4 v[214:217], v[158:159], off offset:16
	v_lshl_add_u64 v[246:247], v[246:247], 0, s[98:99]
	v_lshl_add_u64 v[248:249], v[248:249], 0, s[98:99]
	global_load_dwordx4 v[230:233], v[246:247], off
	global_load_dwordx4 v[234:237], v[246:247], off offset:16
	global_load_dwordx4 v[238:241], v[248:249], off
	global_load_dwordx4 v[242:245], v[248:249], off offset:16
	s_waitcnt vmcnt(4)
	v_pk_mul_f32 v[158:159], v[136:137], v[148:149]
	v_pk_mul_f32 v[160:161], v[134:135], v[146:147]
	v_pk_mul_f32 v[218:219], v[132:133], v[152:153]
	v_pk_mul_f32 v[222:223], v[130:131], v[150:151]
	v_pk_mul_f32 v[224:225], v[144:145], v[148:149]
	v_pk_mul_f32 v[146:147], v[142:143], v[146:147]
	v_pk_mul_f32 v[152:153], v[140:141], v[152:153]
	v_pk_mul_f32 v[226:227], v[138:139], v[150:151]
	v_pk_fma_f32 v[162:163], v[144:145], v[156:157], v[158:159] neg_lo:[0,0,1] neg_hi:[0,0,1]
	v_pk_fma_f32 v[160:161], v[142:143], v[154:155], v[160:161] neg_lo:[0,0,1] neg_hi:[0,0,1]
	v_pk_fma_f32 v[150:151], v[140:141], v[216:217], v[218:219] neg_lo:[0,0,1] neg_hi:[0,0,1]
	v_pk_fma_f32 v[148:149], v[138:139], v[214:215], v[222:223] neg_lo:[0,0,1] neg_hi:[0,0,1]
	v_pk_fma_f32 v[158:159], v[136:137], v[156:157], v[224:225]
	v_pk_fma_f32 v[156:157], v[134:135], v[154:155], v[146:147]
	v_pk_fma_f32 v[154:155], v[132:133], v[216:217], v[152:153]
	v_pk_fma_f32 v[152:153], v[130:131], v[214:215], v[226:227]

;     __host__ __device__ bool next(int i, Unit& u) const {
;         const long L = (long)i * G + c; if (L >= nwg) return false;
;         int wgid = (int)L; { const int q = nwg / NXCD, r = nwg % NXCD, xcd = wgid % NXCD, off = wgid / NXCD; wgid = (xcd < r ? xcd * (q + 1) : r * (q + 1) + (xcd - r) * q) + off; }
;         const int nig = WGM * nN, gid = wgid / nig, fm = gid * WGM, gsz = (nM - fm) < WGM ? (nM - fm) : WGM;
;         u.pm = fm + ((wgid % nig) % gsz); u.pn = (wgid % nig) / gsz; u.sel = 0; return true;
;     __host__ __device__ bool next(int i, Unit& u) const { if (!b.next(i >> 1, u)) return false; u.sel = i & 1; return true; }
.LBB0_721:
	s_ashr_i32 s20, s22, 3
	s_add_i32 s20, s24, s20
	s_ashr_i32 s21, s20, 31
	s_lshr_b32 s21, s21, 29
	s_add_i32 s21, s20, s21
	s_ashr_i32 s22, s21, 3
	s_lshl_b32 s22, s22, 1
	s_and_b32 s21, s21, -8
	s_sub_i32 s21, s20, s21
	s_lshr_b32 s20, s21, 1
	s_and_b32 s21, s21, 1
	s_add_i32 s22, s22, s21
	s_and_b32 s70, s69, 1

;     __host__ __device__ bool next(int i, Unit& u) const { if (!b.next(i >> 1, u)) return false; u.sel = i & 1; return true; }
;     __host__ __device__ bool next(int i, Unit& u) const {
;         const long L = (long)i * G + c; if (L >= nwg) return false;
;         int wgid = (int)L; { const int q = nwg / NXCD, r = nwg % NXCD, xcd = wgid % NXCD, off = wgid / NXCD; wgid = (xcd < r ? xcd * (q + 1) : r * (q + 1) + (xcd - r) * q) + off; }
;         const int nig = WGM * nN, gid = wgid / nig, fm = gid * WGM, gsz = (nM - fm) < WGM ? (nM - fm) : WGM;
;         u.pm = fm + ((wgid % nig) % gsz); u.pn = (wgid % nig) / gsz; u.sel = 0; return true;
.LBB0_836:
	s_ashr_i32 s1, s1, 3
	s_add_i32 s1, s29, s1
	s_ashr_i32 s26, s1, 31
	s_lshr_b32 s26, s26, 29
	s_add_i32 s26, s1, s26
	s_ashr_i32 s27, s26, 3
	s_lshl_b32 s27, s27, 1
	s_and_b32 s26, s26, -8
	s_sub_i32 s1, s1, s26
	s_lshr_b32 s26, s1, 1
	s_and_b32 s1, s1, 1
	s_add_i32 s28, s27, s1

;     __host__ __device__ bool next(int i, Unit& u) const { if (!b.next(i >> 1, u)) return false; u.sel = i & 1; return true; }
;     __host__ __device__ bool next(int i, Unit& u) const {
;         const long L = (long)i * G + c; if (L >= nwg) return false;
;         int wgid = (int)L; { const int q = nwg / NXCD, r = nwg % NXCD, xcd = wgid % NXCD, off = wgid / NXCD; wgid = (xcd < r ? xcd * (q + 1) : r * (q + 1) + (xcd - r) * q) + off; }
;         const int nig = WGM * nN, gid = wgid / nig, fm = gid * WGM, gsz = (nM - fm) < WGM ? (nM - fm) : WGM;
;         u.pm = fm + ((wgid % nig) % gsz); u.pn = (wgid % nig) / gsz; u.sel = 0; return true;
.LBB0_982:
	s_add_i32 s11, s11, 1
	s_mul_i32 s2, s11, s68
	s_mul_hi_u32 s3, s11, s33
	s_add_i32 s3, s3, s2
	s_mul_i32 s2, s11, s33
	s_add_u32 s24, s2, s87
	s_addc_u32 s25, s3, s52
	v_cmp_gt_i64_e32 vcc, s[24:25], v[186:187]
	v_cmp_lt_i64_e64 s[2:3], s[24:25], v[184:185]
	s_cbranch_vccnz .LBB0_984
	s_ashr_i32 s20, s24, 31
	s_lshr_b32 s20, s20, 29
	s_add_i32 s20, s24, s20
	s_ashr_i32 s21, s20, 3
	s_and_b32 s20, s20, -8
	s_sub_i32 s20, s24, s20
	s_cmp_lt_i32 s20, 0
	s_cselect_b32 s22, s53, 0x160
	s_mul_i32 s20, s20, s22
	s_add_i32 s20, s20, s21
	s_mul_hi_i32 s21, s20, 0x2e8ba2e9
	s_lshr_b32 s22, s21, 31
	s_ashr_i32 s21, s21, 3
	s_add_i32 s21, s21, s22
	s_lshl_b32 s22, s21, 1
	s_mul_i32 s21, s21, 44
	s_sub_i32 s21, s20, s21
	s_lshr_b32 s20, s21, 1
	s_and_b32 s21, s21, 1
	s_add_i32 s22, s22, s21

; #define PG8_LAS __attribute__((address_space(3)))
; __device__ __forceinline__ u32x4 pack8(const f32x4 a, const f32x4 b) { u32x4 w; w.x = cvt_pk_bf16(a[0], a[1]); w.y = cvt_pk_bf16(a[2], a[3]); w.z = cvt_pk_bf16(b[0], b[1]); w.w = cvt_pk_bf16(b[2], b[3]); return w; }
; __device__ __forceinline__ float sigm(float v) { return __builtin_amdgcn_rcpf(1.f + __expf(-v)); }
; #define EPI_ROWS _Pragma("unroll") for (int ai = 0; ai < 2; ++ai) _Pragma("unroll") for (int m = 0; m < 4; ++m)
; __device__ __forceinline__ float rstd_lds(const PG8_LAS unsigned char* scr, int lrow) {
;     const PG8_LAS f32x4* p = (const PG8_LAS f32x4*)(scr + lrow * 64);
;     const f32x4 s = (p[0] + p[1]) + (p[2] + p[3]);
;     return __builtin_amdgcn_rsqf(((s[0] + s[1]) + (s[2] + s[3])) * (1.0f / DM) + RMS_EPS);
; }
;     __device__ __forceinline__ void operator()(const f32x4 (&acc)[2][2][4][2], const Unit& u, int wr, int wc, int fr, int fq) const {
;         asm volatile("" : "+v"(fr), "+v"(fq));
;         const int b = u.pm >> 5, tcol = wc * 32 + fq * 8;
;         f32x4 ba0 = {0.f, 0.f, 0.f, 0.f}, ba1 = ba0, bb0 = ba0, bb1 = ba0;
;         if (NORM) { const PG8_LAS float* bp = (const PG8_LAS float*)(scr + 16384) + tcol; ba0 = *(const PG8_LAS f32x4*)bp; ba1 = *(const PG8_LAS f32x4*)(bp + 4); bb0 = *(const PG8_LAS f32x4*)(bp + HALF); bb1 = *(const PG8_LAS f32x4*)(bp + HALF + 4); }
;         float rsv[2][4];
;         if (NORM) { EPI_ROWS { rsv[ai][m] = rstd_lds(scr, EPI_LROW); asm volatile("" : "+v"(rsv[ai][m]) :: "memory"); } }
;         EPI_ROWS { const int row = EPI_ROW;
;             f32x4 a0 = acc[ai][0][m][0], a1 = acc[ai][0][m][1], b0 = acc[ai][1][m][0], b1 = acc[ai][1][m][1];
;             if (NORM) { const float rs = rsv[ai][m]; a0 = a0 * rs + ba0; a1 = a1 * rs + ba1; b0 = b0 * rs + bb0; b1 = b1 * rs + bb1; }
;             f32x4 o0, o1;
; #pragma unroll
;             for (int i = 0; i < 4; ++i) { o0[i] = a0[i] * sigm(a0[i]) * b0[i]; o1[i] = a1[i] * sigm(a1[i]) * b1[i]; }
;             *(u32x4*)(act + (size_t)(row >> 1) * (2 * DFF) + (u.pn * 4 + wc) * 64 + (row & 1) * 32 + fq * 8) = pack8(o0, o1); }
.LBB0_991:
	v_mov_b32_e32 v138, 0xbfb8aa3b
	v_mov_b32_e32 v139, 0xbfb8aa3b
	v_mov_b32_e32 v140, 0x358637bd
	v_lshlrev_b32_e32 v141, 6, v1
	v_lshl_add_u32 v168, v192, 5, s70
	ds_read_b128 v[200:203], v168
	ds_read_b128 v[204:207], v168 offset:16
	ds_read_b128 v[208:211], v168 offset:512
	ds_read_b128 v[212:215], v168 offset:528
	v_lshl_add_u32 v169, v192, 10, v141
	v_add_u32_e32 v169, s71, v169
	ds_read_b128 v[216:219], v169
	ds_read_b128 v[220:223], v169 offset:16
	ds_read_b128 v[224:227], v169 offset:32
	ds_read_b128 v[228:231], v169 offset:48
	ds_read_b128 v[160:163], v169 offset:8192
	ds_read_b128 v[164:167], v169 offset:8208
	ds_read_b128 v[98:101], v169 offset:8224
	ds_read_b128 v[106:109], v169 offset:8240
	s_waitcnt lgkmcnt(4)
	v_pk_add_f32 v[218:219], v[218:219], v[222:223]
	v_pk_add_f32 v[216:217], v[216:217], v[220:221]
	v_pk_add_f32 v[220:221], v[226:227], v[230:231]
	v_pk_add_f32 v[222:223], v[224:225], v[228:229]
	v_pk_add_f32 v[218:219], v[218:219], v[220:221]
	v_pk_add_f32 v[216:217], v[216:217], v[222:223]
	v_add_f32_e32 v216, v216, v217
	v_add_f32_e32 v218, v218, v219
	v_add_f32_e32 v216, v216, v218
	v_fmamk_f32 v216, v216, 0x3a800000, v140
	v_rsq_f32_e32 v216, v216
	s_waitcnt lgkmcnt(0)
	v_pk_add_f32 v[162:163], v[162:163], v[166:167]
	v_pk_add_f32 v[160:161], v[160:161], v[164:165]
	v_pk_add_f32 v[164:165], v[100:101], v[108:109]
	v_pk_add_f32 v[166:167], v[98:99], v[106:107]
	v_pk_add_f32 v[162:163], v[162:163], v[164:165]
	v_pk_add_f32 v[160:161], v[160:161], v[166:167]
	v_add_f32_e32 v160, v160, v161
	v_add_f32_e32 v162, v162, v163
	v_add_f32_e32 v160, v160, v162
	v_fmamk_f32 v160, v160, 0x3a800000, v140
	v_rsq_f32_e32 v160, v160
	v_lshlrev_b32_e32 v220, 2, v1
	v_add_u32_e32 v221, 0x40, v220
	v_add_u32_e32 v222, 0x80, v220
	v_add_u32_e32 v223, 0xc0, v220
	ds_bpermute_b32 v142, v220, v216
	ds_bpermute_b32 v144, v221, v216
	ds_bpermute_b32 v146, v222, v216
	ds_bpermute_b32 v148, v223, v216
	ds_bpermute_b32 v150, v220, v160
	ds_bpermute_b32 v152, v221, v160
	ds_bpermute_b32 v154, v222, v160
	ds_bpermute_b32 v156, v223, v160
	s_waitcnt lgkmcnt(0)
	v_lshrrev_b32_e32 v168, 1, v1
	v_mul_u32_u24_e32 v168, 0x2c00, v168
	v_and_b32_e32 v169, 1, v1
	v_lshl_add_u32 v168, v169, 6, v168
	v_lshl_add_u32 v168, v192, 4, v168
	s_lshl_b32 s21, s28, 8
	s_add_i32 s21, s21, s64
	s_lshr_b32 s21, s21, 1
	s_mul_i32 s21, s21, 0x2c00
	s_or_b32 s28, s34, s67
	s_lshl_b32 s28, s28, 1
	s_add_u32 s21, s21, s28
	s_add_u32 s28, s6, s21
	s_addc_u32 s29, s7, 0
	v_pk_fma_f32 v[134:135], v[134:135], v[142:143], v[200:201] op_sel_hi:[1,0,1]
	v_pk_fma_f32 v[136:137], v[136:137], v[142:143], v[202:203] op_sel_hi:[1,0,1]
	v_pk_fma_f32 v[130:131], v[130:131], v[142:143], v[204:205] op_sel_hi:[1,0,1]
	v_pk_fma_f32 v[132:133], v[132:133], v[142:143], v[206:207] op_sel_hi:[1,0,1]
	v_pk_fma_f32 v[126:127], v[126:127], v[142:143], v[208:209] op_sel_hi:[1,0,1]
	v_pk_fma_f32 v[128:129], v[128:129], v[142:143], v[210:211] op_sel_hi:[1,0,1]
	v_pk_fma_f32 v[122:123], v[122:123], v[142:143], v[212:213] op_sel_hi:[1,0,1]
	v_pk_fma_f32 v[124:125], v[124:125], v[142:143], v[214:215] op_sel_hi:[1,0,1]
	v_pk_mul_f32 v[216:217], v[138:139], v[134:135]
	v_pk_mul_f32 v[218:219], v[138:139], v[136:137]
	v_pk_mul_f32 v[220:221], v[138:139], v[130:131]
	v_pk_mul_f32 v[222:223], v[138:139], v[132:133]
	v_exp_f32_e32 v216, v216
	v_exp_f32_e32 v217, v217
	v_exp_f32_e32 v218, v218
	v_exp_f32_e32 v219, v219
	v_exp_f32_e32 v220, v220
	v_exp_f32_e32 v221, v221
	v_exp_f32_e32 v222, v222
	v_exp_f32_e32 v223, v223
	v_pk_add_f32 v[216:217], v[216:217], 1.0 op_sel_hi:[1,0]
	v_pk_add_f32 v[218:219], v[218:219], 1.0 op_sel_hi:[1,0]
	v_pk_add_f32 v[220:221], v[220:221], 1.0 op_sel_hi:[1,0]
	v_pk_add_f32 v[222:223], v[222:223], 1.0 op_sel_hi:[1,0]
	v_rcp_f32_e32 v216, v216
	v_rcp_f32_e32 v217, v217
	v_rcp_f32_e32 v218, v218
	v_rcp_f32_e32 v219, v219
	v_rcp_f32_e32 v220, v220
	v_rcp_f32_e32 v221, v221
	v_rcp_f32_e32 v222, v222
	v_rcp_f32_e32 v223, v223
	v_pk_mul_f32 v[216:217], v[134:135], v[216:217]
	v_pk_mul_f32 v[218:219], v[136:137], v[218:219]
	v_pk_mul_f32 v[220:221], v[130:131], v[220:221]
	v_pk_mul_f32 v[222:223], v[132:133], v[222:223]
	v_pk_mul_f32 v[216:217], v[216:217], v[126:127]
	v_pk_mul_f32 v[218:219], v[218:219], v[128:129]
	v_pk_mul_f32 v[220:221], v[220:221], v[122:123]
	v_pk_mul_f32 v[222:223], v[222:223], v[124:125]
	v_cvt_pk_bf16_f32 v160, v216, v217
	v_cvt_pk_bf16_f32 v161, v218, v219
	v_cvt_pk_bf16_f32 v162, v220, v221
	v_cvt_pk_bf16_f32 v163, v222, v223
	global_store_dwordx4 v168, v[160:163], s[28:29]
	s_add_u32 s28, s28, 0x16000
	s_addc_u32 s29, s29, 0
	v_pk_fma_f32 v[118:119], v[118:119], v[144:145], v[200:201] op_sel_hi:[1,0,1]
	v_pk_fma_f32 v[120:121], v[120:121], v[144:145], v[202:203] op_sel_hi:[1,0,1]
	v_pk_fma_f32 v[114:115], v[114:115], v[144:145], v[204:205] op_sel_hi:[1,0,1]
	v_pk_fma_f32 v[116:117], v[116:117], v[144:145], v[206:207] op_sel_hi:[1,0,1]
	v_pk_fma_f32 v[110:111], v[110:111], v[144:145], v[208:209] op_sel_hi:[1,0,1]
	v_pk_fma_f32 v[112:113], v[112:113], v[144:145], v[210:211] op_sel_hi:[1,0,1]
	v_pk_fma_f32 v[102:103], v[102:103], v[144:145], v[212:213] op_sel_hi:[1,0,1]
	v_pk_fma_f32 v[104:105], v[104:105], v[144:145], v[214:215] op_sel_hi:[1,0,1]
	v_pk_mul_f32 v[224:225], v[138:139], v[118:119]
	v_pk_mul_f32 v[226:227], v[138:139], v[120:121]
	v_pk_mul_f32 v[228:229], v[138:139], v[114:115]
	v_pk_mul_f32 v[230:231], v[138:139], v[116:117]
	v_exp_f32_e32 v224, v224
	v_exp_f32_e32 v225, v225
	v_exp_f32_e32 v226, v226
	v_exp_f32_e32 v227, v227
	v_exp_f32_e32 v228, v228
	v_exp_f32_e32 v229, v229
	v_exp_f32_e32 v230, v230
	v_exp_f32_e32 v231, v231
; __device__ __forceinline__ u32x4 pack8(const f32x4 a, const f32x4 b) { u32x4 w; w.x = cvt_pk_bf16(a[0], a[1]); w.y = cvt_pk_bf16(a[2], a[3]); w.z = cvt_pk_bf16(b[0], b[1]); w.w = cvt_pk_bf16(b[2], b[3]); return w; }
; __device__ __forceinline__ float sigm(float v) { return __builtin_amdgcn_rcpf(1.f + __expf(-v)); }
; #define EPI_ROWS _Pragma("unroll") for (int ai = 0; ai < 2; ++ai) _Pragma("unroll") for (int m = 0; m < 4; ++m)
;     __device__ __forceinline__ void operator()(const f32x4 (&acc)[2][2][4][2], const Unit& u, int wr, int wc, int fr, int fq) const {
;     ...
;         EPI_ROWS { const int row = EPI_ROW;
;             f32x4 a0 = acc[ai][0][m][0], a1 = acc[ai][0][m][1], b0 = acc[ai][1][m][0], b1 = acc[ai][1][m][1];
;             if (NORM) { const float rs = rsv[ai][m]; a0 = a0 * rs + ba0; a1 = a1 * rs + ba1; b0 = b0 * rs + bb0; b1 = b1 * rs + bb1; }
;             f32x4 o0, o1;
; #pragma unroll
;             for (int i = 0; i < 4; ++i) { o0[i] = a0[i] * sigm(a0[i]) * b0[i]; o1[i] = a1[i] * sigm(a1[i]) * b1[i]; }
;             *(u32x4*)(act + (size_t)(row >> 1) * (2 * DFF) + (u.pn * 4 + wc) * 64 + (row & 1) * 32 + fq * 8) = pack8(o0, o1); }
	v_pk_add_f32 v[224:225], v[224:225], 1.0 op_sel_hi:[1,0]
	v_pk_add_f32 v[226:227], v[226:227], 1.0 op_sel_hi:[1,0]
	v_pk_add_f32 v[228:229], v[228:229], 1.0 op_sel_hi:[1,0]
	v_pk_add_f32 v[230:231], v[230:231], 1.0 op_sel_hi:[1,0]
	v_rcp_f32_e32 v224, v224
	v_rcp_f32_e32 v225, v225
	v_rcp_f32_e32 v226, v226
	v_rcp_f32_e32 v227, v227
	v_rcp_f32_e32 v228, v228
	v_rcp_f32_e32 v229, v229
	v_rcp_f32_e32 v230, v230
	v_rcp_f32_e32 v231, v231
	v_pk_mul_f32 v[224:225], v[118:119], v[224:225]
	v_pk_mul_f32 v[226:227], v[120:121], v[226:227]
	v_pk_mul_f32 v[228:229], v[114:115], v[228:229]
	v_pk_mul_f32 v[230:231], v[116:117], v[230:231]
	v_pk_mul_f32 v[224:225], v[224:225], v[110:111]
	v_pk_mul_f32 v[226:227], v[226:227], v[112:113]
	v_pk_mul_f32 v[228:229], v[228:229], v[102:103]
	v_pk_mul_f32 v[230:231], v[230:231], v[104:105]
	v_cvt_pk_bf16_f32 v164, v224, v225
	v_cvt_pk_bf16_f32 v165, v226, v227
	v_cvt_pk_bf16_f32 v166, v228, v229
	v_cvt_pk_bf16_f32 v167, v230, v231
	global_store_dwordx4 v168, v[164:167], s[28:29]
	s_add_u32 s28, s28, 0x16000
	s_addc_u32 s29, s29, 0
	v_pk_fma_f32 v[94:95], v[94:95], v[146:147], v[200:201] op_sel_hi:[1,0,1]
	v_pk_fma_f32 v[96:97], v[96:97], v[146:147], v[202:203] op_sel_hi:[1,0,1]
	v_pk_fma_f32 v[90:91], v[90:91], v[146:147], v[204:205] op_sel_hi:[1,0,1]
	v_pk_fma_f32 v[92:93], v[92:93], v[146:147], v[206:207] op_sel_hi:[1,0,1]
	v_pk_fma_f32 v[86:87], v[86:87], v[146:147], v[208:209] op_sel_hi:[1,0,1]
	v_pk_fma_f32 v[88:89], v[88:89], v[146:147], v[210:211] op_sel_hi:[1,0,1]
	v_pk_fma_f32 v[82:83], v[82:83], v[146:147], v[212:213] op_sel_hi:[1,0,1]
	v_pk_fma_f32 v[84:85], v[84:85], v[146:147], v[214:215] op_sel_hi:[1,0,1]
	v_pk_mul_f32 v[216:217], v[138:139], v[94:95]
	v_pk_mul_f32 v[218:219], v[138:139], v[96:97]
	v_pk_mul_f32 v[220:221], v[138:139], v[90:91]
	v_pk_mul_f32 v[222:223], v[138:139], v[92:93]
	v_exp_f32_e32 v216, v216
	v_exp_f32_e32 v217, v217
	v_exp_f32_e32 v218, v218
	v_exp_f32_e32 v219, v219
	v_exp_f32_e32 v220, v220
	v_exp_f32_e32 v221, v221
	v_exp_f32_e32 v222, v222
	v_exp_f32_e32 v223, v223
	v_pk_add_f32 v[216:217], v[216:217], 1.0 op_sel_hi:[1,0]
	v_pk_add_f32 v[218:219], v[218:219], 1.0 op_sel_hi:[1,0]
	v_pk_add_f32 v[220:221], v[220:221], 1.0 op_sel_hi:[1,0]
	v_pk_add_f32 v[222:223], v[222:223], 1.0 op_sel_hi:[1,0]
	v_rcp_f32_e32 v216, v216
	v_rcp_f32_e32 v217, v217
	v_rcp_f32_e32 v218, v218
	v_rcp_f32_e32 v219, v219
	v_rcp_f32_e32 v220, v220
	v_rcp_f32_e32 v221, v221
	v_rcp_f32_e32 v222, v222
	v_rcp_f32_e32 v223, v223
	v_pk_mul_f32 v[216:217], v[94:95], v[216:217]
	v_pk_mul_f32 v[218:219], v[96:97], v[218:219]
	v_pk_mul_f32 v[220:221], v[90:91], v[220:221]
	v_pk_mul_f32 v[222:223], v[92:93], v[222:223]
	v_pk_mul_f32 v[216:217], v[216:217], v[86:87]
	v_pk_mul_f32 v[218:219], v[218:219], v[88:89]
	v_pk_mul_f32 v[220:221], v[220:221], v[82:83]
	v_pk_mul_f32 v[222:223], v[222:223], v[84:85]
	v_cvt_pk_bf16_f32 v160, v216, v217
	v_cvt_pk_bf16_f32 v161, v218, v219
	v_cvt_pk_bf16_f32 v162, v220, v221
	v_cvt_pk_bf16_f32 v163, v222, v223
	global_store_dwordx4 v168, v[160:163], s[28:29]
	s_add_u32 s28, s28, 0x16000
	s_addc_u32 s29, s29, 0
	v_pk_fma_f32 v[78:79], v[78:79], v[148:149], v[200:201] op_sel_hi:[1,0,1]
	v_pk_fma_f32 v[80:81], v[80:81], v[148:149], v[202:203] op_sel_hi:[1,0,1]
	v_pk_fma_f32 v[74:75], v[74:75], v[148:149], v[204:205] op_sel_hi:[1,0,1]
	v_pk_fma_f32 v[76:77], v[76:77], v[148:149], v[206:207] op_sel_hi:[1,0,1]
	v_pk_fma_f32 v[70:71], v[70:71], v[148:149], v[208:209] op_sel_hi:[1,0,1]
	v_pk_fma_f32 v[72:73], v[72:73], v[148:149], v[210:211] op_sel_hi:[1,0,1]
	v_pk_fma_f32 v[66:67], v[66:67], v[148:149], v[212:213] op_sel_hi:[1,0,1]
	v_pk_fma_f32 v[68:69], v[68:69], v[148:149], v[214:215] op_sel_hi:[1,0,1]
	v_pk_mul_f32 v[224:225], v[138:139], v[78:79]
	v_pk_mul_f32 v[226:227], v[138:139], v[80:81]
	v_pk_mul_f32 v[228:229], v[138:139], v[74:75]
	v_pk_mul_f32 v[230:231], v[138:139], v[76:77]
	v_exp_f32_e32 v224, v224
	v_exp_f32_e32 v225, v225
	v_exp_f32_e32 v226, v226
	v_exp_f32_e32 v227, v227
	v_exp_f32_e32 v228, v228
	v_exp_f32_e32 v229, v229
	v_exp_f32_e32 v230, v230
	v_exp_f32_e32 v231, v231
	v_pk_add_f32 v[224:225], v[224:225], 1.0 op_sel_hi:[1,0]
	v_pk_add_f32 v[226:227], v[226:227], 1.0 op_sel_hi:[1,0]
	v_pk_add_f32 v[228:229], v[228:229], 1.0 op_sel_hi:[1,0]
	v_pk_add_f32 v[230:231], v[230:231], 1.0 op_sel_hi:[1,0]
	v_rcp_f32_e32 v224, v224
	v_rcp_f32_e32 v225, v225
	v_rcp_f32_e32 v226, v226
	v_rcp_f32_e32 v227, v227
	v_rcp_f32_e32 v228, v228
	v_rcp_f32_e32 v229, v229
	v_rcp_f32_e32 v230, v230
	v_rcp_f32_e32 v231, v231
	v_pk_mul_f32 v[224:225], v[78:79], v[224:225]
	v_pk_mul_f32 v[226:227], v[80:81], v[226:227]
	v_pk_mul_f32 v[228:229], v[74:75], v[228:229]
	v_pk_mul_f32 v[230:231], v[76:77], v[230:231]
	v_pk_mul_f32 v[224:225], v[224:225], v[70:71]
	v_pk_mul_f32 v[226:227], v[226:227], v[72:73]
	v_pk_mul_f32 v[228:229], v[228:229], v[66:67]
	v_pk_mul_f32 v[230:231], v[230:231], v[68:69]
	v_cvt_pk_bf16_f32 v164, v224, v225
	v_cvt_pk_bf16_f32 v165, v226, v227
	v_cvt_pk_bf16_f32 v166, v228, v229
	v_cvt_pk_bf16_f32 v167, v230, v231
	global_store_dwordx4 v168, v[164:167], s[28:29]
	s_add_u32 s28, s28, 0x6e000
	s_addc_u32 s29, s29, 0
	v_pk_fma_f32 v[62:63], v[62:63], v[150:151], v[200:201] op_sel_hi:[1,0,1]
	v_pk_fma_f32 v[64:65], v[64:65], v[150:151], v[202:203] op_sel_hi:[1,0,1]
	v_pk_fma_f32 v[58:59], v[58:59], v[150:151], v[204:205] op_sel_hi:[1,0,1]
	v_pk_fma_f32 v[60:61], v[60:61], v[150:151], v[206:207] op_sel_hi:[1,0,1]
	v_pk_fma_f32 v[54:55], v[54:55], v[150:151], v[208:209] op_sel_hi:[1,0,1]
	v_pk_fma_f32 v[56:57], v[56:57], v[150:151], v[210:211] op_sel_hi:[1,0,1]
; __device__ __forceinline__ u32x4 pack8(const f32x4 a, const f32x4 b) { u32x4 w; w.x = cvt_pk_bf16(a[0], a[1]); w.y = cvt_pk_bf16(a[2], a[3]); w.z = cvt_pk_bf16(b[0], b[1]); w.w = cvt_pk_bf16(b[2], b[3]); return w; }
; __device__ __forceinline__ float sigm(float v) { return __builtin_amdgcn_rcpf(1.f + __expf(-v)); }
; #define EPI_ROWS _Pragma("unroll") for (int ai = 0; ai < 2; ++ai) _Pragma("unroll") for (int m = 0; m < 4; ++m)
;     __device__ __forceinline__ void operator()(const f32x4 (&acc)[2][2][4][2], const Unit& u, int wr, int wc, int fr, int fq) const {
;     ...
;         EPI_ROWS { const int row = EPI_ROW;
;             f32x4 a0 = acc[ai][0][m][0], a1 = acc[ai][0][m][1], b0 = acc[ai][1][m][0], b1 = acc[ai][1][m][1];
;             if (NORM) { const float rs = rsv[ai][m]; a0 = a0 * rs + ba0; a1 = a1 * rs + ba1; b0 = b0 * rs + bb0; b1 = b1 * rs + bb1; }
;             f32x4 o0, o1;
; #pragma unroll
;             for (int i = 0; i < 4; ++i) { o0[i] = a0[i] * sigm(a0[i]) * b0[i]; o1[i] = a1[i] * sigm(a1[i]) * b1[i]; }
;             *(u32x4*)(act + (size_t)(row >> 1) * (2 * DFF) + (u.pn * 4 + wc) * 64 + (row & 1) * 32 + fq * 8) = pack8(o0, o1); }
	v_pk_fma_f32 v[50:51], v[50:51], v[150:151], v[212:213] op_sel_hi:[1,0,1]
	v_pk_fma_f32 v[52:53], v[52:53], v[150:151], v[214:215] op_sel_hi:[1,0,1]
	v_pk_mul_f32 v[216:217], v[138:139], v[62:63]
	v_pk_mul_f32 v[218:219], v[138:139], v[64:65]
	v_pk_mul_f32 v[220:221], v[138:139], v[58:59]
	v_pk_mul_f32 v[222:223], v[138:139], v[60:61]
	v_exp_f32_e32 v216, v216
	v_exp_f32_e32 v217, v217
	v_exp_f32_e32 v218, v218
	v_exp_f32_e32 v219, v219
	v_exp_f32_e32 v220, v220
	v_exp_f32_e32 v221, v221
	v_exp_f32_e32 v222, v222
	v_exp_f32_e32 v223, v223
	v_pk_add_f32 v[216:217], v[216:217], 1.0 op_sel_hi:[1,0]
	v_pk_add_f32 v[218:219], v[218:219], 1.0 op_sel_hi:[1,0]
	v_pk_add_f32 v[220:221], v[220:221], 1.0 op_sel_hi:[1,0]
	v_pk_add_f32 v[222:223], v[222:223], 1.0 op_sel_hi:[1,0]
	v_rcp_f32_e32 v216, v216
	v_rcp_f32_e32 v217, v217
	v_rcp_f32_e32 v218, v218
	v_rcp_f32_e32 v219, v219
	v_rcp_f32_e32 v220, v220
	v_rcp_f32_e32 v221, v221
	v_rcp_f32_e32 v222, v222
	v_rcp_f32_e32 v223, v223
	v_pk_mul_f32 v[216:217], v[62:63], v[216:217]
	v_pk_mul_f32 v[218:219], v[64:65], v[218:219]
	v_pk_mul_f32 v[220:221], v[58:59], v[220:221]
	v_pk_mul_f32 v[222:223], v[60:61], v[222:223]
	v_pk_mul_f32 v[216:217], v[216:217], v[54:55]
	v_pk_mul_f32 v[218:219], v[218:219], v[56:57]
	v_pk_mul_f32 v[220:221], v[220:221], v[50:51]
	v_pk_mul_f32 v[222:223], v[222:223], v[52:53]
	v_cvt_pk_bf16_f32 v160, v216, v217
	v_cvt_pk_bf16_f32 v161, v218, v219
	v_cvt_pk_bf16_f32 v162, v220, v221
	v_cvt_pk_bf16_f32 v163, v222, v223
	global_store_dwordx4 v168, v[160:163], s[28:29]
	s_add_u32 s28, s28, 0x16000
	s_addc_u32 s29, s29, 0
	v_pk_fma_f32 v[46:47], v[46:47], v[152:153], v[200:201] op_sel_hi:[1,0,1]
	v_pk_fma_f32 v[48:49], v[48:49], v[152:153], v[202:203] op_sel_hi:[1,0,1]
	v_pk_fma_f32 v[42:43], v[42:43], v[152:153], v[204:205] op_sel_hi:[1,0,1]
	v_pk_fma_f32 v[44:45], v[44:45], v[152:153], v[206:207] op_sel_hi:[1,0,1]
	v_pk_fma_f32 v[38:39], v[38:39], v[152:153], v[208:209] op_sel_hi:[1,0,1]
	v_pk_fma_f32 v[40:41], v[40:41], v[152:153], v[210:211] op_sel_hi:[1,0,1]
	v_pk_fma_f32 v[34:35], v[34:35], v[152:153], v[212:213] op_sel_hi:[1,0,1]
	v_pk_fma_f32 v[36:37], v[36:37], v[152:153], v[214:215] op_sel_hi:[1,0,1]
	v_pk_mul_f32 v[224:225], v[138:139], v[46:47]
	v_pk_mul_f32 v[226:227], v[138:139], v[48:49]
	v_pk_mul_f32 v[228:229], v[138:139], v[42:43]
	v_pk_mul_f32 v[230:231], v[138:139], v[44:45]
	v_exp_f32_e32 v224, v224
	v_exp_f32_e32 v225, v225
	v_exp_f32_e32 v226, v226
	v_exp_f32_e32 v227, v227
	v_exp_f32_e32 v228, v228
	v_exp_f32_e32 v229, v229
	v_exp_f32_e32 v230, v230
	v_exp_f32_e32 v231, v231
	v_pk_add_f32 v[224:225], v[224:225], 1.0 op_sel_hi:[1,0]
	v_pk_add_f32 v[226:227], v[226:227], 1.0 op_sel_hi:[1,0]
	v_pk_add_f32 v[228:229], v[228:229], 1.0 op_sel_hi:[1,0]
	v_pk_add_f32 v[230:231], v[230:231], 1.0 op_sel_hi:[1,0]
	v_rcp_f32_e32 v224, v224
	v_rcp_f32_e32 v225, v225
	v_rcp_f32_e32 v226, v226
	v_rcp_f32_e32 v227, v227
	v_rcp_f32_e32 v228, v228
	v_rcp_f32_e32 v229, v229
	v_rcp_f32_e32 v230, v230
	v_rcp_f32_e32 v231, v231
	v_pk_mul_f32 v[224:225], v[46:47], v[224:225]
	v_pk_mul_f32 v[226:227], v[48:49], v[226:227]
	v_pk_mul_f32 v[228:229], v[42:43], v[228:229]
	v_pk_mul_f32 v[230:231], v[44:45], v[230:231]
	v_pk_mul_f32 v[224:225], v[224:225], v[38:39]
	v_pk_mul_f32 v[226:227], v[226:227], v[40:41]
	v_pk_mul_f32 v[228:229], v[228:229], v[34:35]
	v_pk_mul_f32 v[230:231], v[230:231], v[36:37]
	v_cvt_pk_bf16_f32 v164, v224, v225
	v_cvt_pk_bf16_f32 v165, v226, v227
	v_cvt_pk_bf16_f32 v166, v228, v229
	v_cvt_pk_bf16_f32 v167, v230, v231
	global_store_dwordx4 v168, v[164:167], s[28:29]
	s_add_u32 s28, s28, 0x16000
	s_addc_u32 s29, s29, 0
	v_pk_fma_f32 v[30:31], v[30:31], v[154:155], v[200:201] op_sel_hi:[1,0,1]
	v_pk_fma_f32 v[32:33], v[32:33], v[154:155], v[202:203] op_sel_hi:[1,0,1]
	v_pk_fma_f32 v[26:27], v[26:27], v[154:155], v[204:205] op_sel_hi:[1,0,1]
	v_pk_fma_f32 v[28:29], v[28:29], v[154:155], v[206:207] op_sel_hi:[1,0,1]
; __device__ __forceinline__ u32x4 pack8(const f32x4 a, const f32x4 b) { u32x4 w; w.x = cvt_pk_bf16(a[0], a[1]); w.y = cvt_pk_bf16(a[2], a[3]); w.z = cvt_pk_bf16(b[0], b[1]); w.w = cvt_pk_bf16(b[2], b[3]); return w; }
; __device__ __forceinline__ float sigm(float v) { return __builtin_amdgcn_rcpf(1.f + __expf(-v)); }
; #define EPI_ROWS _Pragma("unroll") for (int ai = 0; ai < 2; ++ai) _Pragma("unroll") for (int m = 0; m < 4; ++m)
;     __device__ __forceinline__ void operator()(const f32x4 (&acc)[2][2][4][2], const Unit& u, int wr, int wc, int fr, int fq) const {
;     ...
;         EPI_ROWS { const int row = EPI_ROW;
;             f32x4 a0 = acc[ai][0][m][0], a1 = acc[ai][0][m][1], b0 = acc[ai][1][m][0], b1 = acc[ai][1][m][1];
;             if (NORM) { const float rs = rsv[ai][m]; a0 = a0 * rs + ba0; a1 = a1 * rs + ba1; b0 = b0 * rs + bb0; b1 = b1 * rs + bb1; }
;             f32x4 o0, o1;
; #pragma unroll
;             for (int i = 0; i < 4; ++i) { o0[i] = a0[i] * sigm(a0[i]) * b0[i]; o1[i] = a1[i] * sigm(a1[i]) * b1[i]; }
;             *(u32x4*)(act + (size_t)(row >> 1) * (2 * DFF) + (u.pn * 4 + wc) * 64 + (row & 1) * 32 + fq * 8) = pack8(o0, o1); }
	v_pk_fma_f32 v[22:23], v[22:23], v[154:155], v[208:209] op_sel_hi:[1,0,1]
	v_pk_fma_f32 v[24:25], v[24:25], v[154:155], v[210:211] op_sel_hi:[1,0,1]
	v_pk_fma_f32 v[18:19], v[18:19], v[154:155], v[212:213] op_sel_hi:[1,0,1]
	v_pk_fma_f32 v[20:21], v[20:21], v[154:155], v[214:215] op_sel_hi:[1,0,1]
	v_pk_mul_f32 v[216:217], v[138:139], v[30:31]
	v_pk_mul_f32 v[218:219], v[138:139], v[32:33]
	v_pk_mul_f32 v[220:221], v[138:139], v[26:27]
	v_pk_mul_f32 v[222:223], v[138:139], v[28:29]
	v_exp_f32_e32 v216, v216
	v_exp_f32_e32 v217, v217
	v_exp_f32_e32 v218, v218
	v_exp_f32_e32 v219, v219
	v_exp_f32_e32 v220, v220
	v_exp_f32_e32 v221, v221
	v_exp_f32_e32 v222, v222
	v_exp_f32_e32 v223, v223
	v_pk_add_f32 v[216:217], v[216:217], 1.0 op_sel_hi:[1,0]
	v_pk_add_f32 v[218:219], v[218:219], 1.0 op_sel_hi:[1,0]
	v_pk_add_f32 v[220:221], v[220:221], 1.0 op_sel_hi:[1,0]
	v_pk_add_f32 v[222:223], v[222:223], 1.0 op_sel_hi:[1,0]
	v_rcp_f32_e32 v216, v216
	v_rcp_f32_e32 v217, v217
	v_rcp_f32_e32 v218, v218
	v_rcp_f32_e32 v219, v219
	v_rcp_f32_e32 v220, v220
	v_rcp_f32_e32 v221, v221
	v_rcp_f32_e32 v222, v222
	v_rcp_f32_e32 v223, v223
	v_pk_mul_f32 v[216:217], v[30:31], v[216:217]
	v_pk_mul_f32 v[218:219], v[32:33], v[218:219]
	v_pk_mul_f32 v[220:221], v[26:27], v[220:221]
	v_pk_mul_f32 v[222:223], v[28:29], v[222:223]
	v_pk_mul_f32 v[216:217], v[216:217], v[22:23]
	v_pk_mul_f32 v[218:219], v[218:219], v[24:25]
	v_pk_mul_f32 v[220:221], v[220:221], v[18:19]
	v_pk_mul_f32 v[222:223], v[222:223], v[20:21]
	v_cvt_pk_bf16_f32 v160, v216, v217
	v_cvt_pk_bf16_f32 v161, v218, v219
	v_cvt_pk_bf16_f32 v162, v220, v221
	v_cvt_pk_bf16_f32 v163, v222, v223
	global_store_dwordx4 v168, v[160:163], s[28:29]
	s_add_u32 s28, s28, 0x16000
	s_addc_u32 s29, s29, 0
	v_pk_fma_f32 v[14:15], v[14:15], v[156:157], v[200:201] op_sel_hi:[1,0,1]
	v_pk_fma_f32 v[16:17], v[16:17], v[156:157], v[202:203] op_sel_hi:[1,0,1]
	v_pk_fma_f32 v[10:11], v[10:11], v[156:157], v[204:205] op_sel_hi:[1,0,1]
	v_pk_fma_f32 v[12:13], v[12:13], v[156:157], v[206:207] op_sel_hi:[1,0,1]
	v_pk_fma_f32 v[6:7], v[6:7], v[156:157], v[208:209] op_sel_hi:[1,0,1]
	v_pk_fma_f32 v[8:9], v[8:9], v[156:157], v[210:211] op_sel_hi:[1,0,1]
	v_pk_fma_f32 v[2:3], v[2:3], v[156:157], v[212:213] op_sel_hi:[1,0,1]
	v_pk_fma_f32 v[4:5], v[4:5], v[156:157], v[214:215] op_sel_hi:[1,0,1]
	v_pk_mul_f32 v[224:225], v[138:139], v[14:15]
	v_pk_mul_f32 v[226:227], v[138:139], v[16:17]
	v_pk_mul_f32 v[228:229], v[138:139], v[10:11]
	v_pk_mul_f32 v[230:231], v[138:139], v[12:13]
	v_exp_f32_e32 v224, v224
	v_exp_f32_e32 v225, v225
	v_exp_f32_e32 v226, v226
	v_exp_f32_e32 v227, v227
	v_exp_f32_e32 v228, v228
	v_exp_f32_e32 v229, v229
	v_exp_f32_e32 v230, v230
	v_exp_f32_e32 v231, v231
	v_pk_add_f32 v[224:225], v[224:225], 1.0 op_sel_hi:[1,0]
	v_pk_add_f32 v[226:227], v[226:227], 1.0 op_sel_hi:[1,0]
	v_pk_add_f32 v[228:229], v[228:229], 1.0 op_sel_hi:[1,0]
	v_pk_add_f32 v[230:231], v[230:231], 1.0 op_sel_hi:[1,0]
	v_rcp_f32_e32 v224, v224
	v_rcp_f32_e32 v225, v225
	v_rcp_f32_e32 v226, v226
	v_rcp_f32_e32 v227, v227
	v_rcp_f32_e32 v228, v228
	v_rcp_f32_e32 v229, v229
	v_rcp_f32_e32 v230, v230
	v_rcp_f32_e32 v231, v231
	v_pk_mul_f32 v[224:225], v[14:15], v[224:225]
	v_pk_mul_f32 v[226:227], v[16:17], v[226:227]
	v_pk_mul_f32 v[228:229], v[10:11], v[228:229]
	v_pk_mul_f32 v[230:231], v[12:13], v[230:231]
	v_pk_mul_f32 v[224:225], v[224:225], v[6:7]
	v_pk_mul_f32 v[226:227], v[226:227], v[8:9]
	v_pk_mul_f32 v[228:229], v[228:229], v[2:3]
	v_pk_mul_f32 v[230:231], v[230:231], v[4:5]
	v_cvt_pk_bf16_f32 v164, v224, v225
	v_cvt_pk_bf16_f32 v165, v226, v227
	v_cvt_pk_bf16_f32 v166, v228, v229
	v_cvt_pk_bf16_f32 v167, v230, v231
	s_andn2_b64 vcc, exec, s[2:3]
	s_mov_b64 s[2:3], -1
	global_store_dwordx4 v168, v[164:167], s[28:29]
	s_cbranch_vccnz .LBB0_981
	s_andn2_b64 vcc, exec, s[4:5]
	s_cbranch_vccnz .LBB0_980
	s_barrier
	s_branch .LBB0_980

;     __host__ __device__ bool next(int i, Unit& u) const { if (!b.next(i >> 1, u)) return false; u.sel = i & 1; return true; }
;     __host__ __device__ bool next(int i, Unit& u) const {
;         const long L = (long)i * G + c; if (L >= nwg) return false;
;         int wgid = (int)L; { const int q = nwg / NXCD, r = nwg % NXCD, xcd = wgid % NXCD, off = wgid / NXCD; wgid = (xcd < r ? xcd * (q + 1) : r * (q + 1) + (xcd - r) * q) + off; }
;         const int nig = WGM * nN, gid = wgid / nig, fm = gid * WGM, gsz = (nM - fm) < WGM ? (nM - fm) : WGM;
;         u.pm = fm + ((wgid % nig) % gsz); u.pn = (wgid % nig) / gsz; u.sel = 0; return true;
.LBB0_1063:
	s_ashr_i32 s2, s26, 3
	s_add_i32 s2, s28, s2
	s_ashr_i32 s3, s2, 31
	s_lshr_b32 s3, s3, 29
	s_add_i32 s3, s2, s3
	s_ashr_i32 s26, s3, 3
	s_lshl_b32 s26, s26, 1
	s_and_b32 s3, s3, -8
	s_sub_i32 s2, s2, s3
	s_lshr_b32 s65, s2, 1
	s_and_b32 s2, s2, 1
	s_add_i32 s66, s26, s2
